# mLSTM readout prep (mix): gain vector loaded once per wave, next row's operands prefetched during the current row's compute
# baseline (speedup 1.0000x reference)
.LBB0_1800:
	s_or_b64 exec, exec, s[0:1]
	s_movk_i32 s0, 0x4000
	v_cmp_gt_i32_e32 vcc, s0, v72
	s_waitcnt lgkmcnt(0)
	s_barrier
	s_and_saveexec_b64 s[0:1], vcc
	s_cbranch_execz .LBB0_1803
	v_lshlrev_b32_e32 v0, 4, v128
	s_waitcnt vmcnt(2)
	v_and_b32_e32 v4, 0x3f0, v0
	v_mbcnt_lo_u32_b32 v0, -1, 0
	v_mbcnt_hi_u32_b32 v0, -1, v0
	v_and_b32_e32 v3, 64, v0
	v_xor_b32_e32 v2, 1, v0
	v_add_u32_e32 v3, 64, v3
	v_cmp_lt_i32_e32 vcc, v2, v3
	s_add_u32 s6, s86, 0x83b1000
	s_addc_u32 s7, s87, 0
	v_cndmask_b32_e32 v2, v0, v2, vcc
	v_lshlrev_b32_e32 v5, 2, v2
	v_xor_b32_e32 v2, 2, v0
	v_cmp_lt_i32_e32 vcc, v2, v3
	s_add_u32 s8, s86, 0xa3b1000
	s_addc_u32 s9, s87, 0
	v_cndmask_b32_e32 v2, v0, v2, vcc
	v_lshlrev_b32_e32 v10, 2, v2
	v_xor_b32_e32 v2, 4, v0
	v_cmp_lt_i32_e32 vcc, v2, v3
	s_add_u32 s10, s86, 0x6171000
	v_mov_b32_e32 v1, 0
	v_cndmask_b32_e32 v0, v0, v2, vcc
	v_lshlrev_b32_e32 v11, 2, v0
	v_lshlrev_b32_e32 v0, 2, v4
	s_addc_u32 s11, s87, 0
	v_lshl_add_u64 v[6:7], s[76:77], 0, v[0:1]
	s_lshl_b32 s14, s22, 3
	s_mov_b64 s[12:13], 0
	s_waitcnt vmcnt(0)
	v_mov_b32_e32 v12, 0x358637bd
	s_mov_b32 s15, 0x800000
	s_movk_i32 s16, 0x3fff
	global_load_dwordx4 v[100:103], v[6:7], off offset:48
	global_load_dwordx4 v[104:107], v[6:7], off offset:32
	global_load_dwordx4 v[108:111], v[6:7], off offset:16
	global_load_dwordx4 v[112:115], v[6:7], off
	v_ashrrev_i32_e32 v117, 31, v72
	v_mov_b32_e32 v116, v72
	v_lshlrev_b64 v[116:117], 11, v[116:117]
	v_lshl_or_b32 v116, v4, 1, v116
	v_lshl_add_u64 v[118:119], s[6:7], 0, v[116:117]
	global_load_dwordx4 v[76:79], v[118:119], off
	global_load_dwordx4 v[80:83], v[118:119], off offset:16
	v_lshl_add_u64 v[118:119], s[8:9], 0, v[116:117]
	global_load_dwordx4 v[84:87], v[118:119], off
	global_load_dwordx4 v[88:91], v[118:119], off offset:16
	v_lshl_add_u64 v[118:119], s[10:11], 0, v[116:117]
	global_load_dwordx4 v[92:95], v[118:119], off
	global_load_dwordx4 v[96:99], v[118:119], off offset:16
	s_waitcnt vmcnt(0)
	v_mov_b64_e32 v[14:15], v[76:77]
	v_mov_b64_e32 v[16:17], v[78:79]
	v_mov_b64_e32 v[18:19], v[80:81]
	v_mov_b64_e32 v[20:21], v[82:83]
	v_mov_b64_e32 v[22:23], v[84:85]
	v_mov_b64_e32 v[24:25], v[86:87]
	v_mov_b64_e32 v[26:27], v[88:89]
	v_mov_b64_e32 v[28:29], v[90:91]
	v_mov_b64_e32 v[30:31], v[92:93]
	v_mov_b64_e32 v[32:33], v[94:95]
	v_mov_b64_e32 v[34:35], v[96:97]
	v_mov_b64_e32 v[36:37], v[98:99]
	v_mov_b64_e32 v[46:47], v[112:113]
	v_mov_b64_e32 v[48:49], v[114:115]
	v_mov_b64_e32 v[42:43], v[108:109]
	v_mov_b64_e32 v[44:45], v[110:111]
	v_mov_b64_e32 v[38:39], v[104:105]
	v_mov_b64_e32 v[40:41], v[106:107]
	v_mov_b64_e32 v[0:1], v[100:101]
	v_mov_b64_e32 v[2:3], v[102:103]
.LBB0_1802:
	v_ashrrev_i32_e32 v73, 31, v72
	v_lshlrev_b64 v[8:9], 11, v[72:73]
	v_lshl_or_b32 v8, v4, 1, v8
	v_lshl_add_u64 v[50:51], s[10:11], 0, v[8:9]
	v_add_u32_e32 v72, s14, v72
	v_cmp_ge_i32_e32 vcc, s16, v72
	s_and_saveexec_b64 s[98:99], vcc
	v_ashrrev_i32_e32 v117, 31, v72
	v_mov_b32_e32 v116, v72
	v_lshlrev_b64 v[116:117], 11, v[116:117]
	v_lshl_or_b32 v116, v4, 1, v116
	v_lshl_add_u64 v[118:119], s[6:7], 0, v[116:117]
	global_load_dwordx4 v[76:79], v[118:119], off
	global_load_dwordx4 v[80:83], v[118:119], off offset:16
	v_lshl_add_u64 v[118:119], s[8:9], 0, v[116:117]
	global_load_dwordx4 v[84:87], v[118:119], off
	global_load_dwordx4 v[88:91], v[118:119], off offset:16
	v_lshl_add_u64 v[118:119], s[10:11], 0, v[116:117]
	global_load_dwordx4 v[92:95], v[118:119], off
	global_load_dwordx4 v[96:99], v[118:119], off offset:16
	s_mov_b64 exec, s[98:99]
	v_lshl_add_u64 v[8:9], s[88:89], 0, v[8:9]
	v_lshlrev_b32_e32 v67, 16, v30
	v_and_b32_e32 v52, 0xffff0000, v14
	v_and_b32_e32 v60, 0xffff0000, v22
	v_lshlrev_b32_e32 v13, 16, v14
	v_lshlrev_b32_e32 v53, 16, v15
	v_and_b32_e32 v54, 0xffff0000, v15
	v_lshlrev_b32_e32 v55, 16, v16
	v_and_b32_e32 v56, 0xffff0000, v16
	v_lshlrev_b32_e32 v57, 16, v17
	v_and_b32_e32 v58, 0xffff0000, v17
	v_lshlrev_b32_e32 v15, 16, v18
	v_and_b32_e32 v14, 0xffff0000, v18
	v_lshlrev_b32_e32 v17, 16, v19
	v_and_b32_e32 v16, 0xffff0000, v19
	v_lshlrev_b32_e32 v19, 16, v20
	v_and_b32_e32 v18, 0xffff0000, v20
	v_lshlrev_b32_e32 v51, 16, v21
	v_and_b32_e32 v50, 0xffff0000, v21
	v_lshlrev_b32_e32 v59, 16, v22
	v_lshlrev_b32_e32 v61, 16, v23
	v_and_b32_e32 v62, 0xffff0000, v23
	v_lshlrev_b32_e32 v21, 16, v26
	v_and_b32_e32 v20, 0xffff0000, v26
	v_lshlrev_b32_e32 v23, 16, v27
	v_and_b32_e32 v22, 0xffff0000, v27
	v_lshlrev_b32_e32 v27, 16, v29
	v_and_b32_e32 v26, 0xffff0000, v29
	v_add_f32_e32 v52, v52, v60
	v_add_f32_e32 v13, v13, v59
	v_pk_add_f32 v[14:15], v[14:15], v[20:21]
	v_pk_add_f32 v[20:21], v[50:51], v[26:27]
	v_mul_f32_e32 v50, v52, v52
	v_add_f32_e32 v53, v53, v61
	v_fmac_f32_e32 v50, v13, v13
	v_lshlrev_b32_e32 v63, 16, v24
	v_add_f32_e32 v54, v54, v62
	v_fmac_f32_e32 v50, v53, v53
	v_and_b32_e32 v64, 0xffff0000, v24
	v_add_f32_e32 v55, v55, v63
	v_fmac_f32_e32 v50, v54, v54
	v_lshlrev_b32_e32 v65, 16, v25
	v_add_f32_e32 v56, v56, v64
	v_fmac_f32_e32 v50, v55, v55
	v_and_b32_e32 v66, 0xffff0000, v25
	v_add_f32_e32 v57, v57, v65
	v_fmac_f32_e32 v50, v56, v56
	v_add_f32_e32 v58, v58, v66
	v_fmac_f32_e32 v50, v57, v57
	v_pk_add_f32 v[16:17], v[16:17], v[22:23]
	v_pk_mul_f32 v[22:23], v[14:15], v[14:15]
	v_fmac_f32_e32 v50, v58, v58
	v_lshlrev_b32_e32 v25, 16, v28
	v_and_b32_e32 v24, 0xffff0000, v28
	v_add_f32_e32 v23, v23, v50
	v_pk_add_f32 v[18:19], v[18:19], v[24:25]
	v_pk_mul_f32 v[24:25], v[16:17], v[16:17]
	v_add_f32_e32 v22, v22, v23
	v_add_f32_e32 v22, v25, v22
	v_pk_mul_f32 v[26:27], v[18:19], v[18:19]
	v_add_f32_e32 v22, v24, v22
	v_add_f32_e32 v22, v27, v22
	v_pk_mul_f32 v[28:29], v[20:21], v[20:21]
	v_add_f32_e32 v22, v26, v22
	v_add_f32_e32 v22, v29, v22
	v_add_f32_e32 v22, v28, v22
	ds_bpermute_b32 v23, v5, v22
	v_and_b32_e32 v30, 0xffff0000, v30
	v_lshlrev_b32_e32 v68, 16, v31
	v_mul_f32_e32 v24, 0xbfb8aa3b, v67
	v_mul_f32_e32 v25, 0xbfb8aa3b, v30
	s_waitcnt lgkmcnt(0)
	v_add_f32_e32 v22, v22, v23
	ds_bpermute_b32 v23, v10, v22
	v_mul_f32_e32 v26, 0xbfb8aa3b, v68
	v_exp_f32_e32 v24, v24
	v_exp_f32_e32 v25, v25
	v_exp_f32_e32 v26, v26
	s_waitcnt lgkmcnt(0)
	v_add_f32_e32 v22, v22, v23
	ds_bpermute_b32 v23, v11, v22
	v_and_b32_e32 v31, 0xffff0000, v31
	v_mul_f32_e32 v27, 0xbfb8aa3b, v31
	v_exp_f32_e32 v27, v27
	v_add_f32_e32 v24, 1.0, v24
	s_waitcnt lgkmcnt(0)
	v_add_f32_e32 v22, v22, v23
	v_fmamk_f32 v22, v22, 0x3c000000, v12
	v_mul_f32_e32 v23, 0x4b800000, v22
	v_cmp_gt_f32_e32 vcc, s15, v22
	v_add_f32_e32 v25, 1.0, v25
	v_add_f32_e32 v26, 1.0, v26
	v_cndmask_b32_e32 v22, v22, v23, vcc
	v_rsq_f32_e32 v22, v22
	v_rcp_f32_e32 v23, v24
	v_rcp_f32_e32 v24, v25
	v_rcp_f32_e32 v25, v26
	v_mul_f32_e32 v26, 0x45800000, v22
	v_cndmask_b32_e32 v22, v22, v26, vcc
	v_mul_f32_e32 v13, v13, v22
	v_mul_f32_e32 v26, v52, v22
	v_add_f32_e32 v27, 1.0, v27
	v_mul_f32_e32 v13, v46, v13
	v_mul_f32_e32 v26, v47, v26
	v_mul_f32_e32 v13, v23, v13
	v_mul_f32_e32 v23, v24, v26
	v_rcp_f32_e32 v24, v27
	v_mul_f32_e32 v26, v54, v22
	v_lshlrev_b32_e32 v69, 16, v32
	v_mul_f32_e32 v26, v49, v26
	v_mul_f32_e32 v28, v53, v22
	v_mul_f32_e32 v24, v24, v26
	v_mul_f32_e32 v26, 0xbfb8aa3b, v69
	v_and_b32_e32 v32, 0xffff0000, v32
	v_mul_f32_e32 v28, v48, v28
	v_exp_f32_e32 v26, v26
	v_mul_f32_e32 v25, v25, v28
	v_mul_f32_e32 v28, 0xbfb8aa3b, v32
	v_exp_f32_e32 v28, v28
	v_add_f32_e32 v26, 1.0, v26
	v_rcp_f32_e32 v26, v26
	v_mul_f32_e32 v27, v55, v22
	v_add_f32_e32 v28, 1.0, v28
	v_rcp_f32_e32 v28, v28
	v_mul_f32_e32 v27, v42, v27
	v_mul_f32_e32 v26, v26, v27
	v_mul_f32_e32 v27, v56, v22
	v_lshlrev_b32_e32 v70, 16, v33
	v_mul_f32_e32 v27, v43, v27
	v_mul_f32_e32 v27, v28, v27
	v_mul_f32_e32 v28, 0xbfb8aa3b, v70
	v_and_b32_e32 v33, 0xffff0000, v33
	v_exp_f32_e32 v28, v28
	v_mul_f32_e32 v30, 0xbfb8aa3b, v33
	v_exp_f32_e32 v30, v30
	v_mul_f32_e32 v29, v57, v22
	v_add_f32_e32 v28, 1.0, v28
	v_rcp_f32_e32 v28, v28
	v_add_f32_e32 v30, 1.0, v30
	v_rcp_f32_e32 v30, v30
	v_mul_f32_e32 v29, v44, v29
	v_mul_f32_e32 v28, v28, v29
	v_mul_f32_e32 v29, v58, v22
	v_lshlrev_b32_e32 v71, 16, v34
	v_mul_f32_e32 v29, v45, v29
	v_mul_f32_e32 v29, v30, v29
	v_mul_f32_e32 v30, 0xbfb8aa3b, v71
	v_and_b32_e32 v34, 0xffff0000, v34
	v_exp_f32_e32 v30, v30
	v_mul_f32_e32 v31, 0xbfb8aa3b, v34
	v_exp_f32_e32 v31, v31
	v_mul_f32_e32 v15, v15, v22
	v_add_f32_e32 v30, 1.0, v30
	v_rcp_f32_e32 v30, v30
	v_add_f32_e32 v31, 1.0, v31
	v_rcp_f32_e32 v31, v31
	v_lshlrev_b32_e32 v73, 16, v35
	v_mul_f32_e32 v15, v38, v15
	v_mul_f32_e32 v15, v30, v15
	v_mul_f32_e32 v14, v14, v22
	v_mul_f32_e32 v30, 0xbfb8aa3b, v73
	v_and_b32_e32 v35, 0xffff0000, v35
	v_mul_f32_e32 v14, v39, v14
	v_exp_f32_e32 v30, v30
	v_mul_f32_e32 v14, v31, v14
	v_mul_f32_e32 v31, 0xbfb8aa3b, v35
	v_exp_f32_e32 v31, v31
	v_add_f32_e32 v30, 1.0, v30
	v_rcp_f32_e32 v30, v30
	v_mul_f32_e32 v17, v17, v22
	v_add_f32_e32 v31, 1.0, v31
	v_rcp_f32_e32 v31, v31
	v_lshlrev_b32_e32 v74, 16, v36
	v_mul_f32_e32 v17, v40, v17
	v_mul_f32_e32 v17, v30, v17
	v_mul_f32_e32 v16, v16, v22
	v_mul_f32_e32 v30, 0xbfb8aa3b, v74
	v_and_b32_e32 v36, 0xffff0000, v36
	v_mul_f32_e32 v16, v41, v16
	v_exp_f32_e32 v30, v30
	v_mul_f32_e32 v16, v31, v16
	v_mul_f32_e32 v31, 0xbfb8aa3b, v36
	v_exp_f32_e32 v31, v31
	v_add_f32_e32 v30, 1.0, v30
	v_mul_f32_e32 v19, v19, v22
	v_rcp_f32_e32 v30, v30
	v_mul_f32_e32 v0, v19, v0
	v_add_f32_e32 v19, 1.0, v31
	v_rcp_f32_e32 v19, v19
	v_mul_f32_e32 v30, v30, v0
	v_mul_f32_e32 v0, v18, v22
	v_lshlrev_b32_e32 v75, 16, v37
	v_mul_f32_e32 v0, v0, v1
	v_mul_f32_e32 v18, v19, v0
	v_mul_f32_e32 v0, 0xbfb8aa3b, v75
	v_and_b32_e32 v37, 0xffff0000, v37
	v_exp_f32_e32 v0, v0
	v_mul_f32_e32 v19, 0xbfb8aa3b, v37
	v_exp_f32_e32 v19, v19
	v_mul_f32_e32 v1, v21, v22
	v_add_f32_e32 v0, 1.0, v0
	v_rcp_f32_e32 v0, v0
	v_mul_f32_e32 v1, v1, v2
	v_add_f32_e32 v2, 1.0, v19
	v_rcp_f32_e32 v2, v2
	v_mul_f32_e32 v19, v0, v1
	v_mul_f32_e32 v0, v20, v22
	v_mul_f32_e32 v0, v0, v3
	v_cmp_lt_i32_e32 vcc, s16, v72
	v_mul_f32_e32 v20, v2, v0
	v_cvt_pk_bf16_f32 v0, v13, v23
	v_cvt_pk_bf16_f32 v1, v25, v24
	v_cvt_pk_bf16_f32 v2, v26, v27
	v_cvt_pk_bf16_f32 v3, v28, v29
	s_or_b64 s[12:13], vcc, s[12:13]
	global_store_dwordx4 v[8:9], v[0:3], off
	s_nop 1
	v_cvt_pk_bf16_f32 v0, v15, v14
	v_cvt_pk_bf16_f32 v1, v17, v16
	v_cvt_pk_bf16_f32 v2, v30, v18
	v_cvt_pk_bf16_f32 v3, v19, v20
	global_store_dwordx4 v[8:9], v[0:3], off offset:16
	s_waitcnt vmcnt(2)
	v_mov_b64_e32 v[14:15], v[76:77]
	v_mov_b64_e32 v[16:17], v[78:79]
	v_mov_b64_e32 v[18:19], v[80:81]
	v_mov_b64_e32 v[20:21], v[82:83]
	v_mov_b64_e32 v[22:23], v[84:85]
	v_mov_b64_e32 v[24:25], v[86:87]
	v_mov_b64_e32 v[26:27], v[88:89]
	v_mov_b64_e32 v[28:29], v[90:91]
	v_mov_b64_e32 v[30:31], v[92:93]
	v_mov_b64_e32 v[32:33], v[94:95]
	v_mov_b64_e32 v[34:35], v[96:97]
	v_mov_b64_e32 v[36:37], v[98:99]
	v_mov_b64_e32 v[46:47], v[112:113]
	v_mov_b64_e32 v[48:49], v[114:115]
	v_mov_b64_e32 v[42:43], v[108:109]
	v_mov_b64_e32 v[44:45], v[110:111]
	v_mov_b64_e32 v[38:39], v[104:105]
	v_mov_b64_e32 v[40:41], v[106:107]
	v_mov_b64_e32 v[0:1], v[100:101]
	v_mov_b64_e32 v[2:3], v[102:103]
	s_andn2_b64 exec, exec, s[12:13]
	s_cbranch_execnz .LBB0_1802
